# v27 + attention QK: the four K-fragment LDS reads of each key tile issued ahead of their MFMAs (counted lgkmcnt) instead of read-wait-MFMA one at a time
# speedup vs baseline: 1.0062x; 1.0001x over previous
; #define LAS __attribute__((address_space(3)))
; #define LAS __attribute__((address_space(3)))
; #define MFMA32(a, b, c) __builtin_amdgcn_mfma_f32_32x32x16_bf16((a), (b), (c), 0, 0, 0)
; __device__ __forceinline__ void attn_phase_coop(const Params& P, LAS unsigned char* lds, int chunk, int bid, int G, int tid, int wave, int lane, int variant) {
;     ...
;         const int cls = c.ncls == 2 ? (wave >> 2) : 0, qb = c.ncls == 2 ? (wave & 3) : wave;
;         const int mq = c.m0 + 32 * qb + qi;
;         const size_t qrow = (size_t)(c.seq_row0 + mq * c.d + c.r + cls);
;         f32x16 s[5]; int slotj[5]; bool vj[5];
; #pragma unroll
;         for (int j = 0; j < 5; ++j) {
;             const int t = qb + j, kb = c.m0 - 64 + 32 * t;
;             vj[j] = (kb >= 0) && (kb < c.L); slotj[j] = c.ncls == 2 ? cls * 4 + (t - 2) : t;
;             f32x16 a;
; #pragma unroll
;             for (int i = 0; i < 16; ++i) a[i] = vj[j] ? 0.f : -INFINITY;
;             if (vj[j]) {
;                 const LAS unsigned char* kp = lds + CO_K + slotj[j] * 4608 + qi * 144 + hi * 16;
; #pragma unroll
;                 for (int ks = 0; ks < 4; ++ks) { const bf16x8 kf = *(const LAS bf16x8*)(kp + ks * 32); a = MFMA32(kf, qn[ks], a); }
;             }
;             s[j] = a;
;         }
.LBB0_376:
	s_sext_i32_i16 s21, s64
	s_ashr_i32 s94, s63, 9
	s_lshr_b32 s63, s21, 5
	s_and_b64 s[22:23], exec, s[74:75]
	v_readlane_b32 s21, v254, 26
	s_cselect_b32 s44, s27, 0
	s_cselect_b32 s82, s21, s3
	s_lshl_b32 s23, s82, 5
	s_sub_i32 s83, s61, 64
	s_lshl_b32 s21, s44, 2
	s_add_i32 s21, s21, -2
	s_add_i32 s22, s83, s23
	s_cmp_lt_u32 s22, s62
	s_cselect_b64 s[72:73], -1, 0
	s_and_b64 s[64:65], exec, s[74:75]
	s_cselect_b32 s95, s21, 0
	s_add_i32 s64, s95, s82
	v_cndmask_b32_e64 v32, v231, 0, s[72:73]
	s_cmp_ge_u32 s22, s62
	v_mov_b32_e32 v33, v32
	v_mov_b32_e32 v34, v32
	v_mov_b32_e32 v35, v32
	v_mov_b32_e32 v36, v32
	v_mov_b32_e32 v37, v32
	v_mov_b32_e32 v38, v32
	v_mov_b32_e32 v39, v32
	s_cbranch_scc1 .LBB0_378
	s_mul_i32 s21, s64, 0x1200
	v_add_u32_e32 v4, s21, v153
	ds_read_b128 v[0:3], v4
	ds_read_b128 v[236:239], v4 offset:32
	ds_read_b128 v[248:251], v4 offset:64
	v_mov_b32_e32 v40, v32
	v_mov_b32_e32 v41, v32
	v_mov_b32_e32 v42, v32
	v_mov_b32_e32 v43, v32
	v_mov_b32_e32 v44, v32
	v_mov_b32_e32 v45, v32
	v_mov_b32_e32 v46, v32
	v_mov_b32_e32 v47, v32
	s_waitcnt lgkmcnt(2)
	s_nop 0
	v_mfma_f32_32x32x16_bf16 v[32:47], v[0:3], v[84:87], v[32:47]
	ds_read_b128 v[0:3], v4 offset:96
	s_waitcnt lgkmcnt(2)
	v_mfma_f32_32x32x16_bf16 v[32:47], v[236:239], v[88:91], v[32:47]
	s_waitcnt lgkmcnt(1)
	v_mfma_f32_32x32x16_bf16 v[32:47], v[248:251], v[92:95], v[32:47]
	s_waitcnt lgkmcnt(0)
	v_mfma_f32_32x32x16_bf16 v[32:47], v[0:3], v[96:99], v[32:47]
	s_branch .LBB0_379

; #define LAS __attribute__((address_space(3)))
; #define LAS __attribute__((address_space(3)))
; #define MFMA32(a, b, c) __builtin_amdgcn_mfma_f32_32x32x16_bf16((a), (b), (c), 0, 0, 0)
; __device__ __forceinline__ void attn_phase_coop(const Params& P, LAS unsigned char* lds, int chunk, int bid, int G, int tid, int wave, int lane, int variant) {
;     ...
;         for (int j = 0; j < 5; ++j) {
;             const int t = qb + j, kb = c.m0 - 64 + 32 * t;
;             vj[j] = (kb >= 0) && (kb < c.L); slotj[j] = c.ncls == 2 ? cls * 4 + (t - 2) : t;
;             f32x16 a;
; #pragma unroll
;             for (int i = 0; i < 16; ++i) a[i] = vj[j] ? 0.f : -INFINITY;
;             if (vj[j]) {
;                 const LAS unsigned char* kp = lds + CO_K + slotj[j] * 4608 + qi * 144 + hi * 16;
; #pragma unroll
;                 for (int ks = 0; ks < 4; ++ks) { const bf16x8 kf = *(const LAS bf16x8*)(kp + ks * 32); a = MFMA32(kf, qn[ks], a); }
;             }
;             s[j] = a;
;         }
.LBB0_379:
	s_add_i32 s21, s82, 1
	s_lshl_b32 s22, s21, 5
	s_add_i32 s22, s83, s22
	s_cmp_lt_u32 s22, s62
	s_cselect_b64 s[74:75], -1, 0
	v_cndmask_b32_e64 v16, v231, 0, s[74:75]
	s_add_i32 s65, s95, s21
	v_mov_b32_e32 v17, v16
	v_mov_b32_e32 v18, v16
	v_mov_b32_e32 v19, v16
	v_mov_b32_e32 v20, v16
	v_mov_b32_e32 v21, v16
	v_mov_b32_e32 v22, v16
	v_mov_b32_e32 v23, v16
	s_cmp_ge_u32 s22, s62
	s_cbranch_scc1 .LBB0_381
	s_mul_i32 s21, s65, 0x1200
	v_add_u32_e32 v4, s21, v153
	ds_read_b128 v[0:3], v4
	ds_read_b128 v[236:239], v4 offset:32
	ds_read_b128 v[248:251], v4 offset:64
	v_mov_b32_e32 v24, v16
	v_mov_b32_e32 v25, v16
	v_mov_b32_e32 v26, v16
	v_mov_b32_e32 v27, v16
	v_mov_b32_e32 v28, v16
	v_mov_b32_e32 v29, v16
	v_mov_b32_e32 v30, v16
	v_mov_b32_e32 v31, v16
	s_waitcnt lgkmcnt(2)
	s_nop 0
	v_mfma_f32_32x32x16_bf16 v[16:31], v[0:3], v[84:87], v[16:31]
	ds_read_b128 v[0:3], v4 offset:96
	s_waitcnt lgkmcnt(2)
	v_mfma_f32_32x32x16_bf16 v[16:31], v[236:239], v[88:91], v[16:31]
	s_waitcnt lgkmcnt(1)
	v_mfma_f32_32x32x16_bf16 v[16:31], v[248:251], v[92:95], v[16:31]
	s_waitcnt lgkmcnt(0)
	v_mfma_f32_32x32x16_bf16 v[16:31], v[0:3], v[96:99], v[16:31]
	s_branch .LBB0_382

; #define LAS __attribute__((address_space(3)))
; #define LAS __attribute__((address_space(3)))
; #define MFMA32(a, b, c) __builtin_amdgcn_mfma_f32_32x32x16_bf16((a), (b), (c), 0, 0, 0)
; __device__ __forceinline__ void attn_phase_coop(const Params& P, LAS unsigned char* lds, int chunk, int bid, int G, int tid, int wave, int lane, int variant) {
;     ...
;         for (int j = 0; j < 5; ++j) {
;             const int t = qb + j, kb = c.m0 - 64 + 32 * t;
;             vj[j] = (kb >= 0) && (kb < c.L); slotj[j] = c.ncls == 2 ? cls * 4 + (t - 2) : t;
;             f32x16 a;
; #pragma unroll
;             for (int i = 0; i < 16; ++i) a[i] = vj[j] ? 0.f : -INFINITY;
;             if (vj[j]) {
;                 const LAS unsigned char* kp = lds + CO_K + slotj[j] * 4608 + qi * 144 + hi * 16;
; #pragma unroll
;                 for (int ks = 0; ks < 4; ++ks) { const bf16x8 kf = *(const LAS bf16x8*)(kp + ks * 32); a = MFMA32(kf, qn[ks], a); }
;             }
;             s[j] = a;
;         }
.LBB0_382:
	s_add_i32 s21, s82, 2
	s_lshl_b32 s22, s21, 5
	s_add_i32 s22, s83, s22
	s_cmp_lt_u32 s22, s62
	s_cselect_b64 s[76:77], -1, 0
	v_cndmask_b32_e64 v48, v231, 0, s[76:77]
	s_add_i32 s68, s95, s21
	v_mov_b32_e32 v49, v48
	v_mov_b32_e32 v50, v48
	v_mov_b32_e32 v51, v48
	v_mov_b32_e32 v52, v48
	v_mov_b32_e32 v53, v48
	v_mov_b32_e32 v54, v48
	v_mov_b32_e32 v55, v48
	s_cmp_ge_u32 s22, s62
	s_cbranch_scc1 .LBB0_384
	s_mul_i32 s21, s68, 0x1200
	v_add_u32_e32 v4, s21, v153
	ds_read_b128 v[0:3], v4
	ds_read_b128 v[236:239], v4 offset:32
	ds_read_b128 v[248:251], v4 offset:64
	v_mov_b32_e32 v56, v48
	v_mov_b32_e32 v57, v48
	v_mov_b32_e32 v58, v48
	v_mov_b32_e32 v59, v48
	v_mov_b32_e32 v60, v48
	v_mov_b32_e32 v61, v48
	v_mov_b32_e32 v62, v48
	v_mov_b32_e32 v63, v48
	s_waitcnt lgkmcnt(2)
	s_nop 0
	v_mfma_f32_32x32x16_bf16 v[48:63], v[0:3], v[84:87], v[48:63]
	ds_read_b128 v[0:3], v4 offset:96
	s_waitcnt lgkmcnt(2)
	v_mfma_f32_32x32x16_bf16 v[48:63], v[236:239], v[88:91], v[48:63]
	s_waitcnt lgkmcnt(1)
	v_mfma_f32_32x32x16_bf16 v[48:63], v[248:251], v[92:95], v[48:63]
	s_waitcnt lgkmcnt(0)
	v_mfma_f32_32x32x16_bf16 v[48:63], v[0:3], v[96:99], v[48:63]
	s_branch .LBB0_385

; #define LAS __attribute__((address_space(3)))
; #define LAS __attribute__((address_space(3)))
; #define MFMA32(a, b, c) __builtin_amdgcn_mfma_f32_32x32x16_bf16((a), (b), (c), 0, 0, 0)
; __device__ __forceinline__ void attn_phase_coop(const Params& P, LAS unsigned char* lds, int chunk, int bid, int G, int tid, int wave, int lane, int variant) {
;     ...
;         for (int j = 0; j < 5; ++j) {
;             const int t = qb + j, kb = c.m0 - 64 + 32 * t;
;             vj[j] = (kb >= 0) && (kb < c.L); slotj[j] = c.ncls == 2 ? cls * 4 + (t - 2) : t;
;             f32x16 a;
; #pragma unroll
;             for (int i = 0; i < 16; ++i) a[i] = vj[j] ? 0.f : -INFINITY;
;             if (vj[j]) {
;                 const LAS unsigned char* kp = lds + CO_K + slotj[j] * 4608 + qi * 144 + hi * 16;
; #pragma unroll
;                 for (int ks = 0; ks < 4; ++ks) { const bf16x8 kf = *(const LAS bf16x8*)(kp + ks * 32); a = MFMA32(kf, qn[ks], a); }
;             }
;             s[j] = a;
;         }
.LBB0_385:
	s_add_i32 s21, s82, 3
	s_lshl_b32 s22, s21, 5
	s_add_i32 s22, s83, s22
	s_cmp_lt_u32 s22, s62
	s_cselect_b64 s[78:79], -1, 0
	v_cndmask_b32_e64 v0, v231, 0, s[78:79]
	s_add_i32 s69, s95, s21
	v_mov_b32_e32 v1, v0
	v_mov_b32_e32 v2, v0
	v_mov_b32_e32 v3, v0
	v_mov_b32_e32 v4, v0
	v_mov_b32_e32 v5, v0
	v_mov_b32_e32 v6, v0
	v_mov_b32_e32 v7, v0
	s_cmp_ge_u32 s22, s62
	s_cbranch_scc1 .LBB0_387
	s_mul_i32 s21, s69, 0x1200
	v_add_u32_e32 v68, s21, v153
	ds_read_b128 v[64:67], v68
	ds_read_b128 v[236:239], v68 offset:32
	ds_read_b128 v[248:251], v68 offset:64
	v_mov_b32_e32 v8, v0
	v_mov_b32_e32 v9, v0
	v_mov_b32_e32 v10, v0
	v_mov_b32_e32 v11, v0
	v_mov_b32_e32 v12, v0
	v_mov_b32_e32 v13, v0
	v_mov_b32_e32 v14, v0
	v_mov_b32_e32 v15, v0
	s_waitcnt lgkmcnt(2)
	s_nop 0
	v_mfma_f32_32x32x16_bf16 v[0:15], v[64:67], v[84:87], v[0:15]
	ds_read_b128 v[64:67], v68 offset:96
	s_waitcnt lgkmcnt(2)
	v_mfma_f32_32x32x16_bf16 v[0:15], v[236:239], v[88:91], v[0:15]
	s_waitcnt lgkmcnt(1)
	v_mfma_f32_32x32x16_bf16 v[0:15], v[248:251], v[92:95], v[0:15]
	s_waitcnt lgkmcnt(0)
	v_mfma_f32_32x32x16_bf16 v[0:15], v[64:67], v[96:99], v[0:15]
	s_branch .LBB0_388

; #define LAS __attribute__((address_space(3)))
; #define LAS __attribute__((address_space(3)))
; #define MFMA32(a, b, c) __builtin_amdgcn_mfma_f32_32x32x16_bf16((a), (b), (c), 0, 0, 0)
; __device__ __forceinline__ void attn_phase_coop(const Params& P, LAS unsigned char* lds, int chunk, int bid, int G, int tid, int wave, int lane, int variant) {
;     ...
;         for (int j = 0; j < 5; ++j) {
;             const int t = qb + j, kb = c.m0 - 64 + 32 * t;
;             vj[j] = (kb >= 0) && (kb < c.L); slotj[j] = c.ncls == 2 ? cls * 4 + (t - 2) : t;
;             f32x16 a;
; #pragma unroll
;             for (int i = 0; i < 16; ++i) a[i] = vj[j] ? 0.f : -INFINITY;
;             if (vj[j]) {
;                 const LAS unsigned char* kp = lds + CO_K + slotj[j] * 4608 + qi * 144 + hi * 16;
; #pragma unroll
;                 for (int ks = 0; ks < 4; ++ks) { const bf16x8 kf = *(const LAS bf16x8*)(kp + ks * 32); a = MFMA32(kf, qn[ks], a); }
;             }
;             s[j] = a;
;         }
;         if (bu + G < NBU) { const CoopUnit cn = coop_decode(bu + G, S); coop_qload(cn, qkv, wave, qi, hi, qn); }
.LBB0_388:
	s_add_i32 s21, s82, 4
	s_lshl_b32 s22, s21, 5
	s_add_i32 s22, s83, s22
	s_cmp_lt_u32 s22, s62
	s_cselect_b64 s[82:83], -1, 0
	v_cndmask_b32_e64 v64, v231, 0, s[82:83]
	s_add_i32 s95, s95, s21
	v_mov_b32_e32 v65, v64
	v_mov_b32_e32 v66, v64
	v_mov_b32_e32 v67, v64
	v_mov_b32_e32 v68, v64
	v_mov_b32_e32 v69, v64
	v_mov_b32_e32 v70, v64
	v_mov_b32_e32 v71, v64
	s_cmp_ge_u32 s22, s62
	s_cbranch_scc1 .LBB0_390
	s_mul_i32 s21, s95, 0x1200
	v_add_u32_e32 v81, s21, v153
	ds_read_b128 v[162:165], v81
	ds_read_b128 v[236:239], v81 offset:32
	ds_read_b128 v[248:251], v81 offset:64
	v_mov_b32_e32 v72, v64
	v_mov_b32_e32 v73, v64
	v_mov_b32_e32 v74, v64
	v_mov_b32_e32 v75, v64
	v_mov_b32_e32 v76, v64
	v_mov_b32_e32 v77, v64
	v_mov_b32_e32 v78, v64
	v_mov_b32_e32 v79, v64
	s_waitcnt lgkmcnt(2)
	s_nop 0
	v_mfma_f32_32x32x16_bf16 v[64:79], v[162:165], v[84:87], v[64:79]
	ds_read_b128 v[162:165], v81 offset:96
	s_waitcnt lgkmcnt(2)
	v_mfma_f32_32x32x16_bf16 v[64:79], v[236:239], v[88:91], v[64:79]
	s_waitcnt lgkmcnt(1)
	v_mfma_f32_32x32x16_bf16 v[64:79], v[248:251], v[92:95], v[64:79]
	s_waitcnt lgkmcnt(0)
	v_mfma_f32_32x32x16_bf16 v[64:79], v[162:165], v[96:99], v[64:79]
	s_andn2_b64 vcc, exec, s[70:71]
	s_cbranch_vccz .LBB0_391
	s_branch .LBB0_396
